# in-projection GEMM (bias/gelu/stat) epilogue: output stores lane-transposed (data and address via ds_bpermute), deferred one store position
# speedup vs baseline: 1.0095x; 1.0019x over previous
;     __device__ __forceinline__ void operator()(const f32x4 (&acc)[2][2][4][2], const pg8::Unit& u, int wr, int wc, int fr, int fq) const {
;         const int row0 = u.pm * 256 + wr * 64 + fr, col0 = u.pn * 256 + wc * 32 + 8 * fq;
;         const bool do_gelu = u.pn < gelu_tiles, do_stat = u.pn >= stat_tile0;
;         f32x4 bv[2][2];
; #pragma unroll
;         for (int bj = 0; bj < 2; ++bj)
; #pragma unroll
;             for (int n = 0; n < 2; ++n) bv[bj][n] = bias ? *(const f32x4*)(bias + col0 + bj * 128 + 4 * n) : (f32x4){0.f, 0.f, 0.f, 0.f};
.LBB0_240:
	v_and_b32_e32 v238, 63, v163
	v_and_b32_e32 v239, 3, v238
	v_lshrrev_b32_e32 v238, 2, v238
	v_lshl_add_u32 v238, v239, 4, v238
	v_lshlrev_b32_e32 v238, 2, v238
	v_lshl_or_b32 v156, s78, 8, v166
	v_ashrrev_i32_e32 v157, 31, v156
	v_cndmask_b32_e64 v24, 0, 1, s[84:85]
	v_lshl_add_u64 v[158:159], v[156:157], 2, s[22:23]
	v_mov_b32_e32 v40, 0
	v_cmp_ne_u32_e64 s[12:13], 1, v24
	s_andn2_b64 vcc, exec, s[84:85]
	v_mov_b32_e32 v44, 0
	v_mov_b32_e32 v45, 0
	v_mov_b32_e32 v46, 0
	v_mov_b32_e32 v47, 0
	s_cbranch_vccnz .LBB0_242
	global_load_dwordx4 v[44:47], v[158:159], off

; __device__ __forceinline__ unsigned pk2(float lo, float hi) { return pg8::cvt_pk_bf16(lo, hi); }
; __device__ __forceinline__ float gelu_tanh(float x) { const float u = 1.5957691216057308f * (x + 0.044715f * x * x * x); return x * sigmoidf_(u); }
;     __device__ __forceinline__ void operator()(const f32x4 (&acc)[2][2][4][2], const pg8::Unit& u, int wr, int wc, int fr, int fq) const {
;     ...
;             for (int m = 0; m < 4; ++m) {
;                 const int row = row0 + ai * 128 + m * 16;
;                 bf16_t* rowp = O + (size_t)row * ldc + col0;
;                 float s = 0.f, ss = 0.f;
; #pragma unroll
;                 for (int bj = 0; bj < 2; ++bj) {
;                     f32x4 v0 = acc[ai][bj][m][0] + bv[bj][0], v1 = acc[ai][bj][m][1] + bv[bj][1];
;                     if (do_gelu) {
; #pragma unroll
;                         for (int e = 0; e < 4; ++e) { v0[e] = gelu_tanh(v0[e]); v1[e] = gelu_tanh(v1[e]); }
;                     }
; #pragma unroll
;                     for (int e = 0; e < 4; ++e) { s += v0[e] + v1[e]; ss += v0[e] * v0[e] + v1[e] * v1[e]; }
;                     u32x4 w; w.x = pk2(v0[0], v0[1]); w.y = pk2(v0[2], v0[3]); w.z = pk2(v1[0], v1[1]); w.w = pk2(v1[2], v1[3]);
;                     *(u32x4*)(rowp + bj * 128) = w;
;                 }
;                 if (do_stat) {
;                     s += __shfl_xor(s, 16); s += __shfl_xor(s, 32); ss += __shfl_xor(ss, 16); ss += __shfl_xor(ss, 32);
;                     if (fq == 0) STAT[(size_t)row * 32 + (u.pn - stat_tile0) * 4 + wc] = (f32x2){s, ss};
;                 }
.LBB0_250:
	v_lshl_add_u32 v136, s14, 8, v162
	v_mad_i64_i32 v[160:161], s[12:13], v136, s31, 0
	v_lshl_add_u64 v[160:161], v[160:161], 1, s[58:59]
	v_cndmask_b32_e64 v137, 0, 1, s[94:95]
	v_lshl_add_u64 v[160:161], v[156:157], 1, v[160:161]
	v_pk_add_f32 v[134:135], v[134:135], v[30:31]
	v_pk_add_f32 v[132:133], v[132:133], v[28:29]
	v_pk_add_f32 v[130:131], v[130:131], v[26:27]
	v_cmp_ne_u32_e64 s[12:13], 1, v137
	s_andn2_b64 vcc, exec, s[94:95]
	v_pk_add_f32 v[128:129], v[128:129], v[24:25]
	v_cvt_pk_bf16_f32 v188, v140, v141
	v_cvt_pk_bf16_f32 v189, v142, v143
	v_cvt_pk_bf16_f32 v190, v158, v159
	v_cvt_pk_bf16_f32 v191, v138, v139
	ds_bpermute_b32 v240, v238, v160
	ds_bpermute_b32 v241, v238, v161
	ds_bpermute_b32 v242, v238, v188
	ds_bpermute_b32 v243, v238, v189
	ds_bpermute_b32 v244, v238, v190
	ds_bpermute_b32 v245, v238, v191
	s_cbranch_vccnz .LBB0_252
	v_mul_f32_e32 v137, 0x3d372713, v132
	v_mul_f32_e32 v137, v132, v137
	v_fma_f32 v137, v132, v137, v132
	v_mul_f32_e32 v137, 0x3fcc422a, v137
	v_mul_f32_e32 v137, 0xbfb8aa3b, v137
	v_exp_f32_e32 v137, v137
	v_mov_b32_e32 v169, v133
	v_add_f32_e32 v137, 1.0, v137
	v_rcp_f32_e32 v174, v137
	v_mul_f32_e32 v137, 0x3d372713, v128
	v_mul_f32_e32 v137, v128, v137
	v_fma_f32 v137, v128, v137, v128
	v_mul_f32_e32 v137, 0x3fcc422a, v137
	v_mul_f32_e32 v137, 0xbfb8aa3b, v137
	v_exp_f32_e32 v137, v137
	s_nop 0
	v_add_f32_e32 v137, 1.0, v137
	v_rcp_f32_e32 v188, v137
	v_mul_f32_e32 v137, 0x3d372713, v133
	v_mul_f32_e32 v137, v133, v137
	v_fmac_f32_e32 v169, v169, v137
	v_mul_f32_e32 v137, 0x3fcc422a, v169
	v_mul_f32_e32 v137, 0xbfb8aa3b, v137
	v_exp_f32_e32 v137, v137
	v_mov_b32_e32 v169, v129
	v_add_f32_e32 v137, 1.0, v137
	v_rcp_f32_e32 v175, v137
	v_mul_f32_e32 v137, 0x3d372713, v129
	v_mul_f32_e32 v137, v129, v137
	v_fmac_f32_e32 v169, v169, v137
	v_mul_f32_e32 v137, 0x3fcc422a, v169
	v_mul_f32_e32 v137, 0xbfb8aa3b, v137
	v_exp_f32_e32 v137, v137
	v_pk_mul_f32 v[132:133], v[132:133], v[174:175]
	v_add_f32_e32 v137, 1.0, v137
	v_rcp_f32_e32 v189, v137
	v_mul_f32_e32 v137, 0x3d372713, v134
	v_mul_f32_e32 v137, v134, v137
	v_fma_f32 v137, v134, v137, v134
	v_mul_f32_e32 v137, 0x3fcc422a, v137
	v_mul_f32_e32 v137, 0xbfb8aa3b, v137
	v_exp_f32_e32 v137, v137
	v_pk_mul_f32 v[128:129], v[128:129], v[188:189]
	v_add_f32_e32 v137, 1.0, v137
	v_rcp_f32_e32 v190, v137
	v_mul_f32_e32 v137, 0x3d372713, v130
	v_mul_f32_e32 v137, v130, v137
	v_fma_f32 v137, v130, v137, v130
	v_mul_f32_e32 v137, 0x3fcc422a, v137
	v_mul_f32_e32 v137, 0xbfb8aa3b, v137
	v_exp_f32_e32 v137, v137
	s_nop 0
	v_add_f32_e32 v137, 1.0, v137
	v_rcp_f32_e32 v192, v137
	v_mul_f32_e32 v137, 0x3d372713, v135
	v_mul_f32_e32 v137, v135, v137
	v_fma_f32 v137, v135, v137, v135
	v_mul_f32_e32 v137, 0x3fcc422a, v137
	v_mul_f32_e32 v137, 0xbfb8aa3b, v137
	v_exp_f32_e32 v137, v137
	s_nop 0
	v_add_f32_e32 v137, 1.0, v137
	v_rcp_f32_e32 v191, v137
	v_mul_f32_e32 v137, 0x3d372713, v131
	v_mul_f32_e32 v137, v131, v137
	v_fma_f32 v137, v131, v137, v131
	v_mul_f32_e32 v137, 0x3fcc422a, v137
	v_mul_f32_e32 v137, 0xbfb8aa3b, v137
	v_exp_f32_e32 v137, v137
	v_pk_mul_f32 v[134:135], v[134:135], v[190:191]
	v_add_f32_e32 v137, 1.0, v137
	v_rcp_f32_e32 v193, v137
	s_nop 0
	v_pk_mul_f32 v[130:131], v[130:131], v[192:193]
.LBB0_252:
	s_cmp_ge_i32 s78, s24
	v_ashrrev_i32_e32 v137, 31, v136
	s_cselect_b64 s[94:95], -1, 0
	s_cmp_lt_i32 s78, s24
	v_cvt_pk_bf16_f32 v188, v132, v133
	v_cvt_pk_bf16_f32 v189, v134, v135
	v_cvt_pk_bf16_f32 v190, v128, v129
	v_cvt_pk_bf16_f32 v191, v130, v131
	ds_bpermute_b32 v248, v238, v160
	ds_bpermute_b32 v249, v238, v161
	ds_bpermute_b32 v250, v238, v188
	ds_bpermute_b32 v251, v238, v189
	ds_bpermute_b32 v252, v238, v190
	ds_bpermute_b32 v253, v238, v191
	s_waitcnt lgkmcnt(6)
	global_store_dwordx4 v[240:241], v[242:245], off
	s_cbranch_scc1 .LBB0_256
	v_add_f32_e32 v160, v140, v158
	v_mul_f32_e32 v158, v158, v158
	v_fmac_f32_e32 v158, v140, v140
	v_add_f32_e32 v140, v141, v159
	v_mul_f32_e32 v159, v159, v159
	v_fmac_f32_e32 v159, v141, v141
	v_add_f32_e32 v141, v158, v159
	v_add_f32_e32 v158, v142, v138
	v_mul_f32_e32 v138, v138, v138
	v_add_f32_e32 v160, 0, v160
	v_fmac_f32_e32 v138, v142, v142
	v_add_f32_e32 v140, v140, v160
	v_add_f32_e32 v138, v138, v141
	v_add_f32_e32 v141, v143, v139
	v_mul_f32_e32 v139, v139, v139
	v_add_f32_e32 v140, v158, v140
	v_fmac_f32_e32 v139, v143, v143
	v_add_f32_e32 v160, v141, v140
	v_add_f32_e32 v140, v139, v138
	v_pk_mul_f32 v[138:139], v[128:129], v[128:129]
	v_mov_b32_e32 v141, v130
	v_pk_fma_f32 v[138:139], v[132:133], v[132:133], v[138:139]
	v_pk_add_f32 v[128:129], v[132:133], v[128:129]
	v_add_f32_e32 v138, v140, v138
	v_add_f32_e32 v139, v139, v138
	v_mov_b32_e32 v140, v134
	v_mul_f32_e32 v138, v134, v134
	v_pk_fma_f32 v[140:141], v[140:141], v[140:141], v[138:139] op_sel_hi:[1,1,0]
	v_pk_add_f32 v[142:143], v[134:135], v[130:131]
	v_pk_mul_f32 v[158:159], v[134:135], v[134:135]
	v_add_f32_e32 v128, v160, v128
	v_cmp_lt_i32_e32 vcc, v184, v179
	v_mov_b32_e32 v143, v159
	v_mul_f32_e32 v159, v131, v131
	v_add_f32_e32 v158, v129, v128
	v_cndmask_b32_e32 v128, v171, v184, vcc
	v_mov_b32_e32 v140, v135
	v_mov_b32_e32 v138, v131
	v_lshlrev_b32_e32 v132, 2, v128
	v_pk_add_f32 v[128:129], v[142:143], v[158:159]
	v_pk_add_f32 v[130:131], v[140:141], v[138:139]
	v_cmp_lt_i32_e32 vcc, v185, v179
	v_pk_add_f32 v[128:129], v[128:129], v[130:131]
	ds_bpermute_b32 v130, v132, v128
	ds_bpermute_b32 v131, v132, v129
	v_cndmask_b32_e32 v132, v171, v185, vcc
	v_lshlrev_b32_e32 v132, 2, v132
	s_waitcnt lgkmcnt(0)
	v_pk_add_f32 v[128:129], v[128:129], v[130:131]
	ds_bpermute_b32 v130, v132, v128
	ds_bpermute_b32 v131, v132, v129
	s_and_saveexec_b64 s[14:15], s[8:9]
	s_cbranch_execz .LBB0_255
	s_sub_i32 s34, s78, s24
	s_waitcnt lgkmcnt(0)
	v_pk_add_f32 v[128:129], v[128:129], v[130:131]
	s_lshl_b32 s50, s34, 2
	v_lshlrev_b64 v[130:131], 8, v[136:137]
	s_ashr_i32 s51, s50, 31
	v_lshl_add_u64 v[130:131], s[76:77], 0, v[130:131]
	v_lshl_add_u64 v[130:131], s[50:51], 3, v[130:131]
	s_lshl_b32 s34, s17, 3
	v_lshl_add_u64 v[130:131], v[130:131], 0, s[34:35]
	global_store_dwordx2 v[130:131], v[128:129], off

; __device__ __forceinline__ unsigned pk2(float lo, float hi) { return pg8::cvt_pk_bf16(lo, hi); }
; __device__ __forceinline__ float gelu_tanh(float x) { const float u = 1.5957691216057308f * (x + 0.044715f * x * x * x); return x * sigmoidf_(u); }
;     __device__ __forceinline__ void operator()(const f32x4 (&acc)[2][2][4][2], const pg8::Unit& u, int wr, int wc, int fr, int fq) const {
;     ...
;             for (int m = 0; m < 4; ++m) {
;                 const int row = row0 + ai * 128 + m * 16;
;                 bf16_t* rowp = O + (size_t)row * ldc + col0;
;                 float s = 0.f, ss = 0.f;
; #pragma unroll
;                 for (int bj = 0; bj < 2; ++bj) {
;                     f32x4 v0 = acc[ai][bj][m][0] + bv[bj][0], v1 = acc[ai][bj][m][1] + bv[bj][1];
;                     if (do_gelu) {
; #pragma unroll
;                         for (int e = 0; e < 4; ++e) { v0[e] = gelu_tanh(v0[e]); v1[e] = gelu_tanh(v1[e]); }
;                     }
; #pragma unroll
;                     for (int e = 0; e < 4; ++e) { s += v0[e] + v1[e]; ss += v0[e] * v0[e] + v1[e] * v1[e]; }
;                     u32x4 w; w.x = pk2(v0[0], v0[1]); w.y = pk2(v0[2], v0[3]); w.z = pk2(v1[0], v1[1]); w.w = pk2(v1[2], v1[3]);
;                     *(u32x4*)(rowp + bj * 128) = w;
;                 }
;                 if (do_stat) {
;                     s += __shfl_xor(s, 16); s += __shfl_xor(s, 32); ss += __shfl_xor(ss, 16); ss += __shfl_xor(ss, 32);
;                     if (fq == 0) STAT[(size_t)row * 32 + (u.pn - stat_tile0) * 4 + wc] = (f32x2){s, ss};
;                 }
.LBB0_258:
	v_or_b32_e32 v128, 16, v136
	s_waitcnt lgkmcnt(0)
	v_mad_i64_i32 v[130:131], s[14:15], v128, s31, 0
	v_lshl_add_u64 v[130:131], v[130:131], 1, s[58:59]
	v_lshl_add_u64 v[130:131], v[156:157], 1, v[130:131]
	v_pk_add_f32 v[118:119], v[118:119], v[30:31]
	v_pk_add_f32 v[116:117], v[116:117], v[28:29]
	v_pk_add_f32 v[114:115], v[114:115], v[26:27]
	s_and_b64 vcc, exec, s[12:13]
	v_pk_add_f32 v[112:113], v[112:113], v[24:25]
	v_cvt_pk_bf16_f32 v132, v124, v125
	v_cvt_pk_bf16_f32 v133, v126, v127
	v_cvt_pk_bf16_f32 v134, v120, v121
	v_cvt_pk_bf16_f32 v135, v122, v123
	ds_bpermute_b32 v240, v238, v130
	ds_bpermute_b32 v241, v238, v131
	ds_bpermute_b32 v242, v238, v132
	ds_bpermute_b32 v243, v238, v133
	ds_bpermute_b32 v244, v238, v134
	ds_bpermute_b32 v245, v238, v135
	s_waitcnt lgkmcnt(6)
	global_store_dwordx4 v[248:249], v[250:253], off offset:256
	s_cbranch_vccnz .LBB0_260
	v_mul_f32_e32 v129, 0x3d372713, v116
	v_mul_f32_e32 v129, v116, v129
	v_fma_f32 v129, v116, v129, v116
	v_mul_f32_e32 v129, 0x3fcc422a, v129
	v_mul_f32_e32 v129, 0xbfb8aa3b, v129
	v_exp_f32_e32 v129, v129
	v_mov_b32_e32 v133, v117
	v_mov_b32_e32 v135, v113
	v_add_f32_e32 v129, 1.0, v129
	v_rcp_f32_e32 v132, v129
	v_mul_f32_e32 v129, 0x3d372713, v112
	v_mul_f32_e32 v129, v112, v129
	v_fma_f32 v129, v112, v129, v112
	v_mul_f32_e32 v129, 0x3fcc422a, v129
	v_mul_f32_e32 v129, 0xbfb8aa3b, v129
	v_exp_f32_e32 v129, v129
	s_nop 0
	v_add_f32_e32 v129, 1.0, v129
	v_rcp_f32_e32 v134, v129
	v_mul_f32_e32 v129, 0x3d372713, v117
	v_mul_f32_e32 v129, v117, v129
	v_fmac_f32_e32 v133, v133, v129
	v_mul_f32_e32 v129, 0x3fcc422a, v133
	v_mul_f32_e32 v129, 0xbfb8aa3b, v129
	v_exp_f32_e32 v129, v129
	s_nop 0
	v_add_f32_e32 v129, 1.0, v129
	v_rcp_f32_e32 v133, v129
	v_mul_f32_e32 v129, 0x3d372713, v113
	v_mul_f32_e32 v129, v113, v129
	v_fmac_f32_e32 v135, v135, v129
	v_mul_f32_e32 v129, 0x3fcc422a, v135
	v_mul_f32_e32 v129, 0xbfb8aa3b, v129
	v_exp_f32_e32 v129, v129
	v_pk_mul_f32 v[116:117], v[116:117], v[132:133]
	v_add_f32_e32 v129, 1.0, v129
	v_rcp_f32_e32 v135, v129
	v_mul_f32_e32 v129, 0x3d372713, v118
	v_mul_f32_e32 v129, v118, v129
	v_fma_f32 v129, v118, v129, v118
	v_mul_f32_e32 v129, 0x3fcc422a, v129
	v_mul_f32_e32 v129, 0xbfb8aa3b, v129
	v_exp_f32_e32 v129, v129
	v_pk_mul_f32 v[112:113], v[112:113], v[134:135]
	v_add_f32_e32 v129, 1.0, v129
	v_rcp_f32_e32 v138, v129
	v_mul_f32_e32 v129, 0x3d372713, v114
	v_mul_f32_e32 v129, v114, v129
	v_fma_f32 v129, v114, v129, v114
	v_mul_f32_e32 v129, 0x3fcc422a, v129
	v_mul_f32_e32 v129, 0xbfb8aa3b, v129
	v_exp_f32_e32 v129, v129
	s_nop 0
	v_add_f32_e32 v129, 1.0, v129
	v_rcp_f32_e32 v140, v129
	v_mul_f32_e32 v129, 0x3d372713, v119
	v_mul_f32_e32 v129, v119, v129
	v_fma_f32 v129, v119, v129, v119
	v_mul_f32_e32 v129, 0x3fcc422a, v129
	v_mul_f32_e32 v129, 0xbfb8aa3b, v129
	v_exp_f32_e32 v129, v129
	s_nop 0
	v_add_f32_e32 v129, 1.0, v129
	v_rcp_f32_e32 v139, v129
	v_mul_f32_e32 v129, 0x3d372713, v115
	v_mul_f32_e32 v129, v115, v129
	v_fma_f32 v129, v115, v129, v115
	v_mul_f32_e32 v129, 0x3fcc422a, v129
	v_mul_f32_e32 v129, 0xbfb8aa3b, v129
	v_exp_f32_e32 v129, v129
	v_pk_mul_f32 v[118:119], v[118:119], v[138:139]
	v_add_f32_e32 v129, 1.0, v129
	v_rcp_f32_e32 v141, v129
	s_nop 0
	v_pk_mul_f32 v[114:115], v[114:115], v[140:141]
.LBB0_260:
	v_cndmask_b32_e64 v129, 0, 1, s[94:95]
	v_cmp_ne_u32_e64 s[14:15], 1, v129
	s_andn2_b64 vcc, exec, s[94:95]
	v_cvt_pk_bf16_f32 v132, v116, v117
	v_cvt_pk_bf16_f32 v133, v118, v119
	v_cvt_pk_bf16_f32 v134, v112, v113
	v_cvt_pk_bf16_f32 v135, v114, v115
	ds_bpermute_b32 v248, v238, v130
	ds_bpermute_b32 v249, v238, v131
	ds_bpermute_b32 v250, v238, v132
	ds_bpermute_b32 v251, v238, v133
	ds_bpermute_b32 v252, v238, v134
	ds_bpermute_b32 v253, v238, v135
	s_waitcnt lgkmcnt(6)
	global_store_dwordx4 v[240:241], v[242:245], off
	s_cbranch_vccnz .LBB0_264
	v_add_f32_e32 v129, v124, v120
	v_mul_f32_e32 v120, v120, v120
	v_fmac_f32_e32 v120, v124, v124
	v_add_f32_e32 v124, v125, v121
	v_mul_f32_e32 v121, v121, v121
	v_fmac_f32_e32 v121, v125, v125
	v_add_f32_e32 v129, 0, v129
	v_add_f32_e32 v120, v120, v121
	v_add_f32_e32 v121, v126, v122
	v_mul_f32_e32 v122, v122, v122
	v_add_f32_e32 v124, v124, v129
	v_fmac_f32_e32 v122, v126, v126
	v_add_f32_e32 v121, v121, v124
	v_add_f32_e32 v120, v122, v120
	v_add_f32_e32 v122, v127, v123
	v_add_f32_e32 v129, v122, v121
	v_mul_f32_e32 v121, v123, v123
	v_fmac_f32_e32 v121, v127, v127
	v_add_f32_e32 v122, v121, v120
	v_pk_mul_f32 v[120:121], v[112:113], v[112:113]
	v_mov_b32_e32 v123, v114
	v_pk_fma_f32 v[120:121], v[116:117], v[116:117], v[120:121]
	v_pk_add_f32 v[112:113], v[116:117], v[112:113]
	v_add_f32_e32 v120, v122, v120
	v_add_f32_e32 v121, v121, v120
	v_mov_b32_e32 v122, v118
	v_mul_f32_e32 v120, v118, v118
	v_pk_fma_f32 v[122:123], v[122:123], v[122:123], v[120:121] op_sel_hi:[1,1,0]
	v_pk_add_f32 v[124:125], v[118:119], v[114:115]
	v_pk_mul_f32 v[126:127], v[118:119], v[118:119]
	v_add_f32_e32 v112, v129, v112
	v_cmp_lt_i32_e32 vcc, v184, v179
	v_mov_b32_e32 v125, v127
	v_mul_f32_e32 v127, v115, v115
	v_add_f32_e32 v126, v113, v112
	v_cndmask_b32_e32 v112, v171, v184, vcc
	v_mov_b32_e32 v122, v119
	v_mov_b32_e32 v120, v115
	v_lshlrev_b32_e32 v116, 2, v112
	v_pk_add_f32 v[112:113], v[124:125], v[126:127]
	v_pk_add_f32 v[114:115], v[122:123], v[120:121]
	v_cmp_lt_i32_e32 vcc, v185, v179
	v_pk_add_f32 v[112:113], v[112:113], v[114:115]
	ds_bpermute_b32 v114, v116, v112
	ds_bpermute_b32 v115, v116, v113
	v_cndmask_b32_e32 v116, v171, v185, vcc
	v_lshlrev_b32_e32 v116, 2, v116
	s_waitcnt lgkmcnt(0)
	v_pk_add_f32 v[112:113], v[112:113], v[114:115]
	ds_bpermute_b32 v114, v116, v112
	ds_bpermute_b32 v115, v116, v113
	s_and_saveexec_b64 s[94:95], s[8:9]
	s_cbranch_execz .LBB0_263
	v_ashrrev_i32_e32 v129, 31, v128
	s_sub_i32 s34, s78, s24
	s_waitcnt lgkmcnt(0)
	v_pk_add_f32 v[112:113], v[112:113], v[114:115]
	s_lshl_b32 s50, s34, 2
	v_lshlrev_b64 v[114:115], 8, v[128:129]
	s_ashr_i32 s51, s50, 31
	v_lshl_add_u64 v[114:115], s[76:77], 0, v[114:115]
	v_lshl_add_u64 v[114:115], s[50:51], 3, v[114:115]
	s_lshl_b32 s34, s17, 3
	v_lshl_add_u64 v[114:115], v[114:115], 0, s[34:35]
	global_store_dwordx2 v[114:115], v[112:113], off

; __device__ __forceinline__ unsigned pk2(float lo, float hi) { return pg8::cvt_pk_bf16(lo, hi); }
; __device__ __forceinline__ float gelu_tanh(float x) { const float u = 1.5957691216057308f * (x + 0.044715f * x * x * x); return x * sigmoidf_(u); }
;     __device__ __forceinline__ void operator()(const f32x4 (&acc)[2][2][4][2], const pg8::Unit& u, int wr, int wc, int fr, int fq) const {
;     ...
;             for (int m = 0; m < 4; ++m) {
;                 const int row = row0 + ai * 128 + m * 16;
;                 bf16_t* rowp = O + (size_t)row * ldc + col0;
;                 float s = 0.f, ss = 0.f;
; #pragma unroll
;                 for (int bj = 0; bj < 2; ++bj) {
;                     f32x4 v0 = acc[ai][bj][m][0] + bv[bj][0], v1 = acc[ai][bj][m][1] + bv[bj][1];
;                     if (do_gelu) {
; #pragma unroll
;                         for (int e = 0; e < 4; ++e) { v0[e] = gelu_tanh(v0[e]); v1[e] = gelu_tanh(v1[e]); }
;                     }
; #pragma unroll
;                     for (int e = 0; e < 4; ++e) { s += v0[e] + v1[e]; ss += v0[e] * v0[e] + v1[e] * v1[e]; }
;                     u32x4 w; w.x = pk2(v0[0], v0[1]); w.y = pk2(v0[2], v0[3]); w.z = pk2(v1[0], v1[1]); w.w = pk2(v1[2], v1[3]);
;                     *(u32x4*)(rowp + bj * 128) = w;
;                 }
;                 if (do_stat) {
;                     s += __shfl_xor(s, 16); s += __shfl_xor(s, 32); ss += __shfl_xor(ss, 16); ss += __shfl_xor(ss, 32);
;                     if (fq == 0) STAT[(size_t)row * 32 + (u.pn - stat_tile0) * 4 + wc] = (f32x2){s, ss};
;                 }
.LBB0_266:
	v_or_b32_e32 v112, 32, v136
	s_waitcnt lgkmcnt(0)
	v_mad_i64_i32 v[114:115], s[50:51], v112, s31, 0
	v_lshl_add_u64 v[114:115], v[114:115], 1, s[58:59]
	v_lshl_add_u64 v[114:115], v[156:157], 1, v[114:115]
	v_pk_add_f32 v[102:103], v[102:103], v[30:31]
	v_pk_add_f32 v[100:101], v[100:101], v[28:29]
	v_pk_add_f32 v[98:99], v[98:99], v[26:27]
	s_and_b64 vcc, exec, s[12:13]
	v_pk_add_f32 v[96:97], v[96:97], v[24:25]
	v_cvt_pk_bf16_f32 v116, v108, v109
	v_cvt_pk_bf16_f32 v117, v110, v111
	v_cvt_pk_bf16_f32 v118, v104, v105
	v_cvt_pk_bf16_f32 v119, v106, v107
	ds_bpermute_b32 v240, v238, v114
	ds_bpermute_b32 v241, v238, v115
	ds_bpermute_b32 v242, v238, v116
	ds_bpermute_b32 v243, v238, v117
	ds_bpermute_b32 v244, v238, v118
	ds_bpermute_b32 v245, v238, v119
	s_waitcnt lgkmcnt(6)
	global_store_dwordx4 v[248:249], v[250:253], off offset:256
	s_cbranch_vccnz .LBB0_268
	v_mul_f32_e32 v113, 0x3d372713, v100
	v_mul_f32_e32 v113, v100, v113
	v_fma_f32 v113, v100, v113, v100
	v_mul_f32_e32 v113, 0x3fcc422a, v113
	v_mul_f32_e32 v113, 0xbfb8aa3b, v113
	v_exp_f32_e32 v113, v113
	v_mov_b32_e32 v117, v101
	v_mov_b32_e32 v119, v97
	v_add_f32_e32 v113, 1.0, v113
	v_rcp_f32_e32 v116, v113
	v_mul_f32_e32 v113, 0x3d372713, v96
	v_mul_f32_e32 v113, v96, v113
	v_fma_f32 v113, v96, v113, v96
	v_mul_f32_e32 v113, 0x3fcc422a, v113
	v_mul_f32_e32 v113, 0xbfb8aa3b, v113
	v_exp_f32_e32 v113, v113
	s_nop 0
	v_add_f32_e32 v113, 1.0, v113
	v_rcp_f32_e32 v118, v113
	v_mul_f32_e32 v113, 0x3d372713, v101
	v_mul_f32_e32 v113, v101, v113
	v_fmac_f32_e32 v117, v117, v113
	v_mul_f32_e32 v113, 0x3fcc422a, v117
	v_mul_f32_e32 v113, 0xbfb8aa3b, v113
	v_exp_f32_e32 v113, v113
	s_nop 0
	v_add_f32_e32 v113, 1.0, v113
	v_rcp_f32_e32 v117, v113
	v_mul_f32_e32 v113, 0x3d372713, v97
	v_mul_f32_e32 v113, v97, v113
	v_fmac_f32_e32 v119, v119, v113
	v_mul_f32_e32 v113, 0x3fcc422a, v119
	v_mul_f32_e32 v113, 0xbfb8aa3b, v113
	v_exp_f32_e32 v113, v113
	v_pk_mul_f32 v[100:101], v[100:101], v[116:117]
	v_add_f32_e32 v113, 1.0, v113
	v_rcp_f32_e32 v119, v113
	v_mul_f32_e32 v113, 0x3d372713, v102
	v_mul_f32_e32 v113, v102, v113
	v_fma_f32 v113, v102, v113, v102
	v_mul_f32_e32 v113, 0x3fcc422a, v113
	v_mul_f32_e32 v113, 0xbfb8aa3b, v113
	v_exp_f32_e32 v113, v113
	v_pk_mul_f32 v[96:97], v[96:97], v[118:119]
	v_add_f32_e32 v113, 1.0, v113
	v_rcp_f32_e32 v120, v113
	v_mul_f32_e32 v113, 0x3d372713, v98
	v_mul_f32_e32 v113, v98, v113
	v_fma_f32 v113, v98, v113, v98
	v_mul_f32_e32 v113, 0x3fcc422a, v113
	v_mul_f32_e32 v113, 0xbfb8aa3b, v113
	v_exp_f32_e32 v113, v113
	s_nop 0
	v_add_f32_e32 v113, 1.0, v113
	v_rcp_f32_e32 v122, v113
	v_mul_f32_e32 v113, 0x3d372713, v103
	v_mul_f32_e32 v113, v103, v113
	v_fma_f32 v113, v103, v113, v103
	v_mul_f32_e32 v113, 0x3fcc422a, v113
	v_mul_f32_e32 v113, 0xbfb8aa3b, v113
	v_exp_f32_e32 v113, v113
	s_nop 0
	v_add_f32_e32 v113, 1.0, v113
	v_rcp_f32_e32 v121, v113
	v_mul_f32_e32 v113, 0x3d372713, v99
	v_mul_f32_e32 v113, v99, v113
	v_fma_f32 v113, v99, v113, v99
	v_mul_f32_e32 v113, 0x3fcc422a, v113
	v_mul_f32_e32 v113, 0xbfb8aa3b, v113
	v_exp_f32_e32 v113, v113
	v_pk_mul_f32 v[102:103], v[102:103], v[120:121]
	v_add_f32_e32 v113, 1.0, v113
	v_rcp_f32_e32 v123, v113
	s_nop 0
	v_pk_mul_f32 v[98:99], v[98:99], v[122:123]
.LBB0_268:
	s_and_b64 vcc, exec, s[14:15]
	v_cvt_pk_bf16_f32 v116, v100, v101
	v_cvt_pk_bf16_f32 v117, v102, v103
	v_cvt_pk_bf16_f32 v118, v96, v97
	v_cvt_pk_bf16_f32 v119, v98, v99
	ds_bpermute_b32 v248, v238, v114
	ds_bpermute_b32 v249, v238, v115
	ds_bpermute_b32 v250, v238, v116
	ds_bpermute_b32 v251, v238, v117
	ds_bpermute_b32 v252, v238, v118
	ds_bpermute_b32 v253, v238, v119
	s_waitcnt lgkmcnt(6)
	global_store_dwordx4 v[240:241], v[242:245], off
	s_cbranch_vccnz .LBB0_272
	v_add_f32_e32 v113, v108, v104
	v_mul_f32_e32 v104, v104, v104
	v_fmac_f32_e32 v104, v108, v108
	v_add_f32_e32 v108, v109, v105
	v_mul_f32_e32 v105, v105, v105
	v_fmac_f32_e32 v105, v109, v109
	v_add_f32_e32 v113, 0, v113
	v_add_f32_e32 v104, v104, v105
	v_add_f32_e32 v105, v110, v106
	v_mul_f32_e32 v106, v106, v106
	v_add_f32_e32 v108, v108, v113
	v_fmac_f32_e32 v106, v110, v110
	v_add_f32_e32 v105, v105, v108
	v_add_f32_e32 v104, v106, v104
	v_add_f32_e32 v106, v111, v107
	v_add_f32_e32 v113, v106, v105
	v_mul_f32_e32 v105, v107, v107
	v_fmac_f32_e32 v105, v111, v111
	v_add_f32_e32 v106, v105, v104
	v_pk_mul_f32 v[104:105], v[96:97], v[96:97]
	v_mov_b32_e32 v107, v98
	v_pk_fma_f32 v[104:105], v[100:101], v[100:101], v[104:105]
	v_pk_add_f32 v[96:97], v[100:101], v[96:97]
	v_add_f32_e32 v104, v106, v104
	v_add_f32_e32 v105, v105, v104
	v_mov_b32_e32 v106, v102
	v_mul_f32_e32 v104, v102, v102
	v_pk_fma_f32 v[106:107], v[106:107], v[106:107], v[104:105] op_sel_hi:[1,1,0]
	v_pk_add_f32 v[108:109], v[102:103], v[98:99]
	v_pk_mul_f32 v[110:111], v[102:103], v[102:103]
	v_add_f32_e32 v96, v113, v96
	v_cmp_lt_i32_e32 vcc, v184, v179
	v_mov_b32_e32 v109, v111
	v_mul_f32_e32 v111, v99, v99
	v_add_f32_e32 v110, v97, v96
	v_cndmask_b32_e32 v96, v171, v184, vcc
	v_mov_b32_e32 v106, v103
	v_mov_b32_e32 v104, v99
	v_lshlrev_b32_e32 v100, 2, v96
	v_pk_add_f32 v[96:97], v[108:109], v[110:111]
	v_pk_add_f32 v[98:99], v[106:107], v[104:105]
	v_cmp_lt_i32_e32 vcc, v185, v179
	v_pk_add_f32 v[96:97], v[96:97], v[98:99]
	ds_bpermute_b32 v98, v100, v96
	ds_bpermute_b32 v99, v100, v97
	v_cndmask_b32_e32 v100, v171, v185, vcc
	v_lshlrev_b32_e32 v100, 2, v100
	s_waitcnt lgkmcnt(0)
	v_pk_add_f32 v[96:97], v[96:97], v[98:99]
	ds_bpermute_b32 v98, v100, v96
	ds_bpermute_b32 v99, v100, v97
	s_and_saveexec_b64 s[94:95], s[8:9]
	s_cbranch_execz .LBB0_271
	v_ashrrev_i32_e32 v113, 31, v112
	s_sub_i32 s34, s78, s24
	s_waitcnt lgkmcnt(0)
	v_pk_add_f32 v[96:97], v[96:97], v[98:99]
	s_lshl_b32 s50, s34, 2
	v_lshlrev_b64 v[98:99], 8, v[112:113]
	s_ashr_i32 s51, s50, 31
	v_lshl_add_u64 v[98:99], s[76:77], 0, v[98:99]
	v_lshl_add_u64 v[98:99], s[50:51], 3, v[98:99]
	s_lshl_b32 s34, s17, 3
	v_lshl_add_u64 v[98:99], v[98:99], 0, s[34:35]
	global_store_dwordx2 v[98:99], v[96:97], off

; __device__ __forceinline__ unsigned pk2(float lo, float hi) { return pg8::cvt_pk_bf16(lo, hi); }
; __device__ __forceinline__ float gelu_tanh(float x) { const float u = 1.5957691216057308f * (x + 0.044715f * x * x * x); return x * sigmoidf_(u); }
;     __device__ __forceinline__ void operator()(const f32x4 (&acc)[2][2][4][2], const pg8::Unit& u, int wr, int wc, int fr, int fq) const {
;     ...
;             for (int m = 0; m < 4; ++m) {
;                 const int row = row0 + ai * 128 + m * 16;
;                 bf16_t* rowp = O + (size_t)row * ldc + col0;
;                 float s = 0.f, ss = 0.f;
; #pragma unroll
;                 for (int bj = 0; bj < 2; ++bj) {
;                     f32x4 v0 = acc[ai][bj][m][0] + bv[bj][0], v1 = acc[ai][bj][m][1] + bv[bj][1];
;                     if (do_gelu) {
; #pragma unroll
;                         for (int e = 0; e < 4; ++e) { v0[e] = gelu_tanh(v0[e]); v1[e] = gelu_tanh(v1[e]); }
;                     }
; #pragma unroll
;                     for (int e = 0; e < 4; ++e) { s += v0[e] + v1[e]; ss += v0[e] * v0[e] + v1[e] * v1[e]; }
;                     u32x4 w; w.x = pk2(v0[0], v0[1]); w.y = pk2(v0[2], v0[3]); w.z = pk2(v1[0], v1[1]); w.w = pk2(v1[2], v1[3]);
;                     *(u32x4*)(rowp + bj * 128) = w;
;                 }
;                 if (do_stat) {
;                     s += __shfl_xor(s, 16); s += __shfl_xor(s, 32); ss += __shfl_xor(ss, 16); ss += __shfl_xor(ss, 32);
;                     if (fq == 0) STAT[(size_t)row * 32 + (u.pn - stat_tile0) * 4 + wc] = (f32x2){s, ss};
;                 }
.LBB0_274:
	v_or_b32_e32 v96, 48, v136
	s_waitcnt lgkmcnt(0)
	v_mad_i64_i32 v[98:99], s[50:51], v96, s31, 0
	v_lshl_add_u64 v[98:99], v[98:99], 1, s[58:59]
	v_lshl_add_u64 v[98:99], v[156:157], 1, v[98:99]
	v_pk_add_f32 v[86:87], v[86:87], v[30:31]
	v_pk_add_f32 v[84:85], v[84:85], v[28:29]
	v_pk_add_f32 v[82:83], v[82:83], v[26:27]
	s_and_b64 vcc, exec, s[12:13]
	v_pk_add_f32 v[80:81], v[80:81], v[24:25]
	v_cvt_pk_bf16_f32 v100, v92, v93
	v_cvt_pk_bf16_f32 v101, v94, v95
	v_cvt_pk_bf16_f32 v102, v88, v89
	v_cvt_pk_bf16_f32 v103, v90, v91
	ds_bpermute_b32 v240, v238, v98
	ds_bpermute_b32 v241, v238, v99
	ds_bpermute_b32 v242, v238, v100
	ds_bpermute_b32 v243, v238, v101
	ds_bpermute_b32 v244, v238, v102
	ds_bpermute_b32 v245, v238, v103
	s_waitcnt lgkmcnt(6)
	global_store_dwordx4 v[248:249], v[250:253], off offset:256
	s_cbranch_vccnz .LBB0_276
	v_mul_f32_e32 v97, 0x3d372713, v84
	v_mul_f32_e32 v97, v84, v97
	v_fma_f32 v97, v84, v97, v84
	v_mul_f32_e32 v97, 0x3fcc422a, v97
	v_mul_f32_e32 v97, 0xbfb8aa3b, v97
	v_exp_f32_e32 v97, v97
	v_mov_b32_e32 v101, v85
	v_mov_b32_e32 v103, v81
	v_add_f32_e32 v97, 1.0, v97
	v_rcp_f32_e32 v100, v97
	v_mul_f32_e32 v97, 0x3d372713, v80
	v_mul_f32_e32 v97, v80, v97
	v_fma_f32 v97, v80, v97, v80
	v_mul_f32_e32 v97, 0x3fcc422a, v97
	v_mul_f32_e32 v97, 0xbfb8aa3b, v97
	v_exp_f32_e32 v97, v97
	s_nop 0
	v_add_f32_e32 v97, 1.0, v97
	v_rcp_f32_e32 v102, v97
	v_mul_f32_e32 v97, 0x3d372713, v85
	v_mul_f32_e32 v97, v85, v97
	v_fmac_f32_e32 v101, v101, v97
	v_mul_f32_e32 v97, 0x3fcc422a, v101
	v_mul_f32_e32 v97, 0xbfb8aa3b, v97
	v_exp_f32_e32 v97, v97
	s_nop 0
	v_add_f32_e32 v97, 1.0, v97
	v_rcp_f32_e32 v101, v97
	v_mul_f32_e32 v97, 0x3d372713, v81
	v_mul_f32_e32 v97, v81, v97
	v_fmac_f32_e32 v103, v103, v97
	v_mul_f32_e32 v97, 0x3fcc422a, v103
	v_mul_f32_e32 v97, 0xbfb8aa3b, v97
	v_exp_f32_e32 v97, v97
	v_pk_mul_f32 v[84:85], v[84:85], v[100:101]
	v_add_f32_e32 v97, 1.0, v97
	v_rcp_f32_e32 v103, v97
	v_mul_f32_e32 v97, 0x3d372713, v86
	v_mul_f32_e32 v97, v86, v97
	v_fma_f32 v97, v86, v97, v86
	v_mul_f32_e32 v97, 0x3fcc422a, v97
	v_mul_f32_e32 v97, 0xbfb8aa3b, v97
	v_exp_f32_e32 v97, v97
	v_pk_mul_f32 v[80:81], v[80:81], v[102:103]
	v_add_f32_e32 v97, 1.0, v97
	v_rcp_f32_e32 v104, v97
	v_mul_f32_e32 v97, 0x3d372713, v82
	v_mul_f32_e32 v97, v82, v97
	v_fma_f32 v97, v82, v97, v82
	v_mul_f32_e32 v97, 0x3fcc422a, v97
	v_mul_f32_e32 v97, 0xbfb8aa3b, v97
	v_exp_f32_e32 v97, v97
	s_nop 0
	v_add_f32_e32 v97, 1.0, v97
	v_rcp_f32_e32 v106, v97
	v_mul_f32_e32 v97, 0x3d372713, v87
	v_mul_f32_e32 v97, v87, v97
	v_fma_f32 v97, v87, v97, v87
	v_mul_f32_e32 v97, 0x3fcc422a, v97
	v_mul_f32_e32 v97, 0xbfb8aa3b, v97
	v_exp_f32_e32 v97, v97
	s_nop 0
	v_add_f32_e32 v97, 1.0, v97
	v_rcp_f32_e32 v105, v97
	v_mul_f32_e32 v97, 0x3d372713, v83
	v_mul_f32_e32 v97, v83, v97
	v_fma_f32 v97, v83, v97, v83
	v_mul_f32_e32 v97, 0x3fcc422a, v97
	v_mul_f32_e32 v97, 0xbfb8aa3b, v97
	v_exp_f32_e32 v97, v97
	v_pk_mul_f32 v[86:87], v[86:87], v[104:105]
	v_add_f32_e32 v97, 1.0, v97
	v_rcp_f32_e32 v107, v97
	s_nop 0
	v_pk_mul_f32 v[82:83], v[82:83], v[106:107]
.LBB0_276:
	s_and_b64 vcc, exec, s[14:15]
	v_cvt_pk_bf16_f32 v100, v84, v85
	v_cvt_pk_bf16_f32 v101, v86, v87
	v_cvt_pk_bf16_f32 v102, v80, v81
	v_cvt_pk_bf16_f32 v103, v82, v83
	ds_bpermute_b32 v248, v238, v98
	ds_bpermute_b32 v249, v238, v99
	ds_bpermute_b32 v250, v238, v100
	ds_bpermute_b32 v251, v238, v101
	ds_bpermute_b32 v252, v238, v102
	ds_bpermute_b32 v253, v238, v103
	s_waitcnt lgkmcnt(6)
	global_store_dwordx4 v[240:241], v[242:245], off
	s_cbranch_vccnz .LBB0_280
	v_add_f32_e32 v97, v92, v88
	v_mul_f32_e32 v88, v88, v88
	v_fmac_f32_e32 v88, v92, v92
	v_add_f32_e32 v92, v93, v89
	v_mul_f32_e32 v89, v89, v89
	v_fmac_f32_e32 v89, v93, v93
	v_add_f32_e32 v97, 0, v97
	v_add_f32_e32 v88, v88, v89
	v_add_f32_e32 v89, v94, v90
	v_mul_f32_e32 v90, v90, v90
	v_add_f32_e32 v92, v92, v97
	v_fmac_f32_e32 v90, v94, v94
	v_add_f32_e32 v89, v89, v92
	v_add_f32_e32 v88, v90, v88
	v_add_f32_e32 v90, v95, v91
	v_add_f32_e32 v97, v90, v89
	v_mul_f32_e32 v89, v91, v91
	v_fmac_f32_e32 v89, v95, v95
	v_add_f32_e32 v90, v89, v88
	v_pk_mul_f32 v[88:89], v[80:81], v[80:81]
	v_mov_b32_e32 v91, v82
	v_pk_fma_f32 v[88:89], v[84:85], v[84:85], v[88:89]
	v_pk_add_f32 v[80:81], v[84:85], v[80:81]
	v_add_f32_e32 v88, v90, v88
	v_add_f32_e32 v89, v89, v88
	v_mov_b32_e32 v90, v86
	v_mul_f32_e32 v88, v86, v86
	v_pk_fma_f32 v[90:91], v[90:91], v[90:91], v[88:89] op_sel_hi:[1,1,0]
	v_pk_add_f32 v[92:93], v[86:87], v[82:83]
	v_pk_mul_f32 v[94:95], v[86:87], v[86:87]
	v_add_f32_e32 v80, v97, v80
	v_cmp_lt_i32_e32 vcc, v184, v179
	v_mov_b32_e32 v93, v95
	v_mul_f32_e32 v95, v83, v83
	v_add_f32_e32 v94, v81, v80
	v_cndmask_b32_e32 v80, v171, v184, vcc
	v_mov_b32_e32 v90, v87
	v_mov_b32_e32 v88, v83
	v_lshlrev_b32_e32 v84, 2, v80
	v_pk_add_f32 v[80:81], v[92:93], v[94:95]
	v_pk_add_f32 v[82:83], v[90:91], v[88:89]
	v_cmp_lt_i32_e32 vcc, v185, v179
	v_pk_add_f32 v[80:81], v[80:81], v[82:83]
	ds_bpermute_b32 v82, v84, v80
	ds_bpermute_b32 v83, v84, v81
	v_cndmask_b32_e32 v84, v171, v185, vcc
	v_lshlrev_b32_e32 v84, 2, v84
	s_waitcnt lgkmcnt(0)
	v_pk_add_f32 v[80:81], v[80:81], v[82:83]
	ds_bpermute_b32 v82, v84, v80
	ds_bpermute_b32 v83, v84, v81
	s_and_saveexec_b64 s[94:95], s[8:9]
	s_cbranch_execz .LBB0_279
	v_ashrrev_i32_e32 v97, 31, v96
	s_sub_i32 s34, s78, s24
	s_waitcnt lgkmcnt(0)
	v_pk_add_f32 v[80:81], v[80:81], v[82:83]
	s_lshl_b32 s50, s34, 2
	v_lshlrev_b64 v[82:83], 8, v[96:97]
	s_ashr_i32 s51, s50, 31
	v_lshl_add_u64 v[82:83], s[76:77], 0, v[82:83]
	v_lshl_add_u64 v[82:83], s[50:51], 3, v[82:83]
	s_lshl_b32 s34, s17, 3
	v_lshl_add_u64 v[82:83], v[82:83], 0, s[34:35]
	global_store_dwordx2 v[82:83], v[80:81], off

; __device__ __forceinline__ unsigned pk2(float lo, float hi) { return pg8::cvt_pk_bf16(lo, hi); }
; __device__ __forceinline__ float gelu_tanh(float x) { const float u = 1.5957691216057308f * (x + 0.044715f * x * x * x); return x * sigmoidf_(u); }
;     __device__ __forceinline__ void operator()(const f32x4 (&acc)[2][2][4][2], const pg8::Unit& u, int wr, int wc, int fr, int fq) const {
;     ...
;             for (int m = 0; m < 4; ++m) {
;                 const int row = row0 + ai * 128 + m * 16;
;                 bf16_t* rowp = O + (size_t)row * ldc + col0;
;                 float s = 0.f, ss = 0.f;
; #pragma unroll
;                 for (int bj = 0; bj < 2; ++bj) {
;                     f32x4 v0 = acc[ai][bj][m][0] + bv[bj][0], v1 = acc[ai][bj][m][1] + bv[bj][1];
;                     if (do_gelu) {
; #pragma unroll
;                         for (int e = 0; e < 4; ++e) { v0[e] = gelu_tanh(v0[e]); v1[e] = gelu_tanh(v1[e]); }
;                     }
; #pragma unroll
;                     for (int e = 0; e < 4; ++e) { s += v0[e] + v1[e]; ss += v0[e] * v0[e] + v1[e] * v1[e]; }
;                     u32x4 w; w.x = pk2(v0[0], v0[1]); w.y = pk2(v0[2], v0[3]); w.z = pk2(v1[0], v1[1]); w.w = pk2(v1[2], v1[3]);
;                     *(u32x4*)(rowp + bj * 128) = w;
;                 }
;                 if (do_stat) {
;                     s += __shfl_xor(s, 16); s += __shfl_xor(s, 32); ss += __shfl_xor(ss, 16); ss += __shfl_xor(ss, 32);
;                     if (fq == 0) STAT[(size_t)row * 32 + (u.pn - stat_tile0) * 4 + wc] = (f32x2){s, ss};
;                 }
.LBB0_282:
	v_add_u32_e32 v80, 0x80, v136
	s_waitcnt lgkmcnt(0)
	v_mad_i64_i32 v[82:83], s[50:51], v80, s31, 0
	v_lshl_add_u64 v[82:83], v[82:83], 1, s[58:59]
	v_lshl_add_u64 v[82:83], v[156:157], 1, v[82:83]
	v_pk_add_f32 v[70:71], v[70:71], v[30:31]
	v_pk_add_f32 v[68:69], v[68:69], v[28:29]
	v_pk_add_f32 v[66:67], v[66:67], v[26:27]
	s_and_b64 vcc, exec, s[12:13]
	v_pk_add_f32 v[64:65], v[64:65], v[24:25]
	v_cvt_pk_bf16_f32 v84, v76, v77
	v_cvt_pk_bf16_f32 v85, v78, v79
	v_cvt_pk_bf16_f32 v86, v72, v73
	v_cvt_pk_bf16_f32 v87, v74, v75
	ds_bpermute_b32 v240, v238, v82
	ds_bpermute_b32 v241, v238, v83
	ds_bpermute_b32 v242, v238, v84
	ds_bpermute_b32 v243, v238, v85
	ds_bpermute_b32 v244, v238, v86
	ds_bpermute_b32 v245, v238, v87
	s_waitcnt lgkmcnt(6)
	global_store_dwordx4 v[248:249], v[250:253], off offset:256
	s_cbranch_vccnz .LBB0_284
	v_mul_f32_e32 v81, 0x3d372713, v68
	v_mul_f32_e32 v81, v68, v81
	v_fma_f32 v81, v68, v81, v68
	v_mul_f32_e32 v81, 0x3fcc422a, v81
	v_mul_f32_e32 v81, 0xbfb8aa3b, v81
	v_exp_f32_e32 v81, v81
	v_mov_b32_e32 v85, v69
	v_mov_b32_e32 v87, v65
	v_add_f32_e32 v81, 1.0, v81
	v_rcp_f32_e32 v84, v81
	v_mul_f32_e32 v81, 0x3d372713, v64
	v_mul_f32_e32 v81, v64, v81
	v_fma_f32 v81, v64, v81, v64
	v_mul_f32_e32 v81, 0x3fcc422a, v81
	v_mul_f32_e32 v81, 0xbfb8aa3b, v81
	v_exp_f32_e32 v81, v81
	s_nop 0
	v_add_f32_e32 v81, 1.0, v81
	v_rcp_f32_e32 v86, v81
	v_mul_f32_e32 v81, 0x3d372713, v69
	v_mul_f32_e32 v81, v69, v81
	v_fmac_f32_e32 v85, v85, v81
	v_mul_f32_e32 v81, 0x3fcc422a, v85
	v_mul_f32_e32 v81, 0xbfb8aa3b, v81
	v_exp_f32_e32 v81, v81
	s_nop 0
	v_add_f32_e32 v81, 1.0, v81
	v_rcp_f32_e32 v85, v81
	v_mul_f32_e32 v81, 0x3d372713, v65
	v_mul_f32_e32 v81, v65, v81
	v_fmac_f32_e32 v87, v87, v81
	v_mul_f32_e32 v81, 0x3fcc422a, v87
	v_mul_f32_e32 v81, 0xbfb8aa3b, v81
	v_exp_f32_e32 v81, v81
	v_pk_mul_f32 v[68:69], v[68:69], v[84:85]
	v_add_f32_e32 v81, 1.0, v81
	v_rcp_f32_e32 v87, v81
	v_mul_f32_e32 v81, 0x3d372713, v70
	v_mul_f32_e32 v81, v70, v81
	v_fma_f32 v81, v70, v81, v70
	v_mul_f32_e32 v81, 0x3fcc422a, v81
	v_mul_f32_e32 v81, 0xbfb8aa3b, v81
	v_exp_f32_e32 v81, v81
	v_pk_mul_f32 v[64:65], v[64:65], v[86:87]
	v_add_f32_e32 v81, 1.0, v81
	v_rcp_f32_e32 v88, v81
	v_mul_f32_e32 v81, 0x3d372713, v66
	v_mul_f32_e32 v81, v66, v81
	v_fma_f32 v81, v66, v81, v66
	v_mul_f32_e32 v81, 0x3fcc422a, v81
	v_mul_f32_e32 v81, 0xbfb8aa3b, v81
	v_exp_f32_e32 v81, v81
	s_nop 0
	v_add_f32_e32 v81, 1.0, v81
	v_rcp_f32_e32 v90, v81
	v_mul_f32_e32 v81, 0x3d372713, v71
	v_mul_f32_e32 v81, v71, v81
	v_fma_f32 v81, v71, v81, v71
	v_mul_f32_e32 v81, 0x3fcc422a, v81
	v_mul_f32_e32 v81, 0xbfb8aa3b, v81
	v_exp_f32_e32 v81, v81
	s_nop 0
	v_add_f32_e32 v81, 1.0, v81
	v_rcp_f32_e32 v89, v81
	v_mul_f32_e32 v81, 0x3d372713, v67
	v_mul_f32_e32 v81, v67, v81
	v_fma_f32 v81, v67, v81, v67
	v_mul_f32_e32 v81, 0x3fcc422a, v81
	v_mul_f32_e32 v81, 0xbfb8aa3b, v81
	v_exp_f32_e32 v81, v81
	v_pk_mul_f32 v[70:71], v[70:71], v[88:89]
	v_add_f32_e32 v81, 1.0, v81
	v_rcp_f32_e32 v91, v81
	s_nop 0
	v_pk_mul_f32 v[66:67], v[66:67], v[90:91]
.LBB0_284:
	s_and_b64 vcc, exec, s[14:15]
	v_cvt_pk_bf16_f32 v84, v68, v69
	v_cvt_pk_bf16_f32 v85, v70, v71
	v_cvt_pk_bf16_f32 v86, v64, v65
	v_cvt_pk_bf16_f32 v87, v66, v67
	ds_bpermute_b32 v248, v238, v82
	ds_bpermute_b32 v249, v238, v83
	ds_bpermute_b32 v250, v238, v84
	ds_bpermute_b32 v251, v238, v85
	ds_bpermute_b32 v252, v238, v86
	ds_bpermute_b32 v253, v238, v87
	s_waitcnt lgkmcnt(6)
	global_store_dwordx4 v[240:241], v[242:245], off
	s_cbranch_vccnz .LBB0_288
	v_add_f32_e32 v81, v76, v72
	v_mul_f32_e32 v72, v72, v72
	v_fmac_f32_e32 v72, v76, v76
	v_add_f32_e32 v76, v77, v73
	v_mul_f32_e32 v73, v73, v73
	v_fmac_f32_e32 v73, v77, v77
	v_add_f32_e32 v81, 0, v81
	v_add_f32_e32 v72, v72, v73
	v_add_f32_e32 v73, v78, v74
	v_mul_f32_e32 v74, v74, v74
	v_add_f32_e32 v76, v76, v81
	v_fmac_f32_e32 v74, v78, v78
	v_add_f32_e32 v73, v73, v76
	v_add_f32_e32 v72, v74, v72
	v_add_f32_e32 v74, v79, v75
	v_add_f32_e32 v81, v74, v73
	v_mul_f32_e32 v73, v75, v75
	v_fmac_f32_e32 v73, v79, v79
	v_add_f32_e32 v74, v73, v72
	v_pk_mul_f32 v[72:73], v[64:65], v[64:65]
	v_mov_b32_e32 v75, v66
	v_pk_fma_f32 v[72:73], v[68:69], v[68:69], v[72:73]
	v_pk_add_f32 v[64:65], v[68:69], v[64:65]
	v_add_f32_e32 v72, v74, v72
	v_add_f32_e32 v73, v73, v72
	v_mov_b32_e32 v74, v70
	v_mul_f32_e32 v72, v70, v70
	v_pk_fma_f32 v[74:75], v[74:75], v[74:75], v[72:73] op_sel_hi:[1,1,0]
	v_pk_add_f32 v[76:77], v[70:71], v[66:67]
	v_pk_mul_f32 v[78:79], v[70:71], v[70:71]
	v_add_f32_e32 v64, v81, v64
	v_cmp_lt_i32_e32 vcc, v184, v179
	v_mov_b32_e32 v77, v79
	v_mul_f32_e32 v79, v67, v67
	v_add_f32_e32 v78, v65, v64
	v_cndmask_b32_e32 v64, v171, v184, vcc
	v_mov_b32_e32 v74, v71
	v_mov_b32_e32 v72, v67
	v_lshlrev_b32_e32 v68, 2, v64
	v_pk_add_f32 v[64:65], v[76:77], v[78:79]
	v_pk_add_f32 v[66:67], v[74:75], v[72:73]
	v_cmp_lt_i32_e32 vcc, v185, v179
	v_pk_add_f32 v[64:65], v[64:65], v[66:67]
	ds_bpermute_b32 v66, v68, v64
	ds_bpermute_b32 v67, v68, v65
	v_cndmask_b32_e32 v68, v171, v185, vcc
	v_lshlrev_b32_e32 v68, 2, v68
	s_waitcnt lgkmcnt(0)
	v_pk_add_f32 v[64:65], v[64:65], v[66:67]
	ds_bpermute_b32 v66, v68, v64
	ds_bpermute_b32 v67, v68, v65
	s_and_saveexec_b64 s[94:95], s[8:9]
	s_cbranch_execz .LBB0_287
	v_ashrrev_i32_e32 v81, 31, v80
	s_sub_i32 s34, s78, s24
	s_waitcnt lgkmcnt(0)
	v_pk_add_f32 v[64:65], v[64:65], v[66:67]
	s_lshl_b32 s50, s34, 2
	v_lshlrev_b64 v[66:67], 8, v[80:81]
	s_ashr_i32 s51, s50, 31
	v_lshl_add_u64 v[66:67], s[76:77], 0, v[66:67]
	v_lshl_add_u64 v[66:67], s[50:51], 3, v[66:67]
	s_lshl_b32 s34, s17, 3
	v_lshl_add_u64 v[66:67], v[66:67], 0, s[34:35]
	global_store_dwordx2 v[66:67], v[64:65], off

; __device__ __forceinline__ unsigned pk2(float lo, float hi) { return pg8::cvt_pk_bf16(lo, hi); }
; __device__ __forceinline__ float gelu_tanh(float x) { const float u = 1.5957691216057308f * (x + 0.044715f * x * x * x); return x * sigmoidf_(u); }
;     __device__ __forceinline__ void operator()(const f32x4 (&acc)[2][2][4][2], const pg8::Unit& u, int wr, int wc, int fr, int fq) const {
;     ...
;             for (int m = 0; m < 4; ++m) {
;                 const int row = row0 + ai * 128 + m * 16;
;                 bf16_t* rowp = O + (size_t)row * ldc + col0;
;                 float s = 0.f, ss = 0.f;
; #pragma unroll
;                 for (int bj = 0; bj < 2; ++bj) {
;                     f32x4 v0 = acc[ai][bj][m][0] + bv[bj][0], v1 = acc[ai][bj][m][1] + bv[bj][1];
;                     if (do_gelu) {
; #pragma unroll
;                         for (int e = 0; e < 4; ++e) { v0[e] = gelu_tanh(v0[e]); v1[e] = gelu_tanh(v1[e]); }
;                     }
; #pragma unroll
;                     for (int e = 0; e < 4; ++e) { s += v0[e] + v1[e]; ss += v0[e] * v0[e] + v1[e] * v1[e]; }
;                     u32x4 w; w.x = pk2(v0[0], v0[1]); w.y = pk2(v0[2], v0[3]); w.z = pk2(v1[0], v1[1]); w.w = pk2(v1[2], v1[3]);
;                     *(u32x4*)(rowp + bj * 128) = w;
;                 }
;                 if (do_stat) {
;                     s += __shfl_xor(s, 16); s += __shfl_xor(s, 32); ss += __shfl_xor(ss, 16); ss += __shfl_xor(ss, 32);
;                     if (fq == 0) STAT[(size_t)row * 32 + (u.pn - stat_tile0) * 4 + wc] = (f32x2){s, ss};
;                 }
.LBB0_290:
	v_add_u32_e32 v64, 0x90, v136
	s_waitcnt lgkmcnt(0)
	v_mad_i64_i32 v[66:67], s[50:51], v64, s31, 0
	v_lshl_add_u64 v[66:67], v[66:67], 1, s[58:59]
	v_lshl_add_u64 v[66:67], v[156:157], 1, v[66:67]
	v_pk_add_f32 v[54:55], v[54:55], v[30:31]
	v_pk_add_f32 v[52:53], v[52:53], v[28:29]
	v_pk_add_f32 v[50:51], v[50:51], v[26:27]
	s_and_b64 vcc, exec, s[12:13]
	v_pk_add_f32 v[48:49], v[48:49], v[24:25]
	v_cvt_pk_bf16_f32 v68, v60, v61
	v_cvt_pk_bf16_f32 v69, v62, v63
	v_cvt_pk_bf16_f32 v70, v56, v57
	v_cvt_pk_bf16_f32 v71, v58, v59
	ds_bpermute_b32 v240, v238, v66
	ds_bpermute_b32 v241, v238, v67
	ds_bpermute_b32 v242, v238, v68
	ds_bpermute_b32 v243, v238, v69
	ds_bpermute_b32 v244, v238, v70
	ds_bpermute_b32 v245, v238, v71
	s_waitcnt lgkmcnt(6)
	global_store_dwordx4 v[248:249], v[250:253], off offset:256
	s_cbranch_vccnz .LBB0_292
	v_mul_f32_e32 v65, 0x3d372713, v52
	v_mul_f32_e32 v65, v52, v65
	v_fma_f32 v65, v52, v65, v52
	v_mul_f32_e32 v65, 0x3fcc422a, v65
	v_mul_f32_e32 v65, 0xbfb8aa3b, v65
	v_exp_f32_e32 v65, v65
	v_mov_b32_e32 v69, v53
	v_mov_b32_e32 v71, v49
	v_add_f32_e32 v65, 1.0, v65
	v_rcp_f32_e32 v68, v65
	v_mul_f32_e32 v65, 0x3d372713, v48
	v_mul_f32_e32 v65, v48, v65
	v_fma_f32 v65, v48, v65, v48
	v_mul_f32_e32 v65, 0x3fcc422a, v65
	v_mul_f32_e32 v65, 0xbfb8aa3b, v65
	v_exp_f32_e32 v65, v65
	s_nop 0
	v_add_f32_e32 v65, 1.0, v65
	v_rcp_f32_e32 v70, v65
	v_mul_f32_e32 v65, 0x3d372713, v53
	v_mul_f32_e32 v65, v53, v65
	v_fmac_f32_e32 v69, v69, v65
	v_mul_f32_e32 v65, 0x3fcc422a, v69
	v_mul_f32_e32 v65, 0xbfb8aa3b, v65
	v_exp_f32_e32 v65, v65
	s_nop 0
	v_add_f32_e32 v65, 1.0, v65
	v_rcp_f32_e32 v69, v65
	v_mul_f32_e32 v65, 0x3d372713, v49
	v_mul_f32_e32 v65, v49, v65
	v_fmac_f32_e32 v71, v71, v65
	v_mul_f32_e32 v65, 0x3fcc422a, v71
	v_mul_f32_e32 v65, 0xbfb8aa3b, v65
	v_exp_f32_e32 v65, v65
	v_pk_mul_f32 v[52:53], v[52:53], v[68:69]
	v_add_f32_e32 v65, 1.0, v65
	v_rcp_f32_e32 v71, v65
	v_mul_f32_e32 v65, 0x3d372713, v54
	v_mul_f32_e32 v65, v54, v65
	v_fma_f32 v65, v54, v65, v54
	v_mul_f32_e32 v65, 0x3fcc422a, v65
	v_mul_f32_e32 v65, 0xbfb8aa3b, v65
	v_exp_f32_e32 v65, v65
	v_pk_mul_f32 v[48:49], v[48:49], v[70:71]
	v_add_f32_e32 v65, 1.0, v65
	v_rcp_f32_e32 v72, v65
	v_mul_f32_e32 v65, 0x3d372713, v50
	v_mul_f32_e32 v65, v50, v65
	v_fma_f32 v65, v50, v65, v50
	v_mul_f32_e32 v65, 0x3fcc422a, v65
	v_mul_f32_e32 v65, 0xbfb8aa3b, v65
	v_exp_f32_e32 v65, v65
	s_nop 0
	v_add_f32_e32 v65, 1.0, v65
	v_rcp_f32_e32 v74, v65
	v_mul_f32_e32 v65, 0x3d372713, v55
	v_mul_f32_e32 v65, v55, v65
	v_fma_f32 v65, v55, v65, v55
	v_mul_f32_e32 v65, 0x3fcc422a, v65
	v_mul_f32_e32 v65, 0xbfb8aa3b, v65
	v_exp_f32_e32 v65, v65
	s_nop 0
	v_add_f32_e32 v65, 1.0, v65
	v_rcp_f32_e32 v73, v65
	v_mul_f32_e32 v65, 0x3d372713, v51
	v_mul_f32_e32 v65, v51, v65
	v_fma_f32 v65, v51, v65, v51
	v_mul_f32_e32 v65, 0x3fcc422a, v65
	v_mul_f32_e32 v65, 0xbfb8aa3b, v65
	v_exp_f32_e32 v65, v65
	v_pk_mul_f32 v[54:55], v[54:55], v[72:73]
	v_add_f32_e32 v65, 1.0, v65
	v_rcp_f32_e32 v75, v65
	s_nop 0
	v_pk_mul_f32 v[50:51], v[50:51], v[74:75]
.LBB0_292:
	s_and_b64 vcc, exec, s[14:15]
	v_cvt_pk_bf16_f32 v68, v52, v53
	v_cvt_pk_bf16_f32 v69, v54, v55
	v_cvt_pk_bf16_f32 v70, v48, v49
	v_cvt_pk_bf16_f32 v71, v50, v51
	ds_bpermute_b32 v248, v238, v66
	ds_bpermute_b32 v249, v238, v67
	ds_bpermute_b32 v250, v238, v68
	ds_bpermute_b32 v251, v238, v69
	ds_bpermute_b32 v252, v238, v70
	ds_bpermute_b32 v253, v238, v71
	s_waitcnt lgkmcnt(6)
	global_store_dwordx4 v[240:241], v[242:245], off
	s_cbranch_vccnz .LBB0_296
	v_add_f32_e32 v65, v60, v56
	v_mul_f32_e32 v56, v56, v56
	v_fmac_f32_e32 v56, v60, v60
	v_add_f32_e32 v60, v61, v57
	v_mul_f32_e32 v57, v57, v57
	v_fmac_f32_e32 v57, v61, v61
	v_add_f32_e32 v65, 0, v65
	v_add_f32_e32 v56, v56, v57
	v_add_f32_e32 v57, v62, v58
	v_mul_f32_e32 v58, v58, v58
	v_add_f32_e32 v60, v60, v65
	v_fmac_f32_e32 v58, v62, v62
	v_add_f32_e32 v57, v57, v60
	v_add_f32_e32 v56, v58, v56
	v_add_f32_e32 v58, v63, v59
	v_add_f32_e32 v65, v58, v57
	v_mul_f32_e32 v57, v59, v59
	v_fmac_f32_e32 v57, v63, v63
	v_add_f32_e32 v58, v57, v56
	v_pk_mul_f32 v[56:57], v[48:49], v[48:49]
	v_mov_b32_e32 v59, v50
	v_pk_fma_f32 v[56:57], v[52:53], v[52:53], v[56:57]
	v_pk_add_f32 v[48:49], v[52:53], v[48:49]
	v_add_f32_e32 v56, v58, v56
	v_add_f32_e32 v57, v57, v56
	v_mov_b32_e32 v58, v54
	v_mul_f32_e32 v56, v54, v54
	v_pk_fma_f32 v[58:59], v[58:59], v[58:59], v[56:57] op_sel_hi:[1,1,0]
	v_pk_add_f32 v[60:61], v[54:55], v[50:51]
	v_pk_mul_f32 v[62:63], v[54:55], v[54:55]
	v_add_f32_e32 v48, v65, v48
	v_cmp_lt_i32_e32 vcc, v184, v179
	v_mov_b32_e32 v61, v63
	v_mul_f32_e32 v63, v51, v51
	v_add_f32_e32 v62, v49, v48
	v_cndmask_b32_e32 v48, v171, v184, vcc
	v_mov_b32_e32 v58, v55
	v_mov_b32_e32 v56, v51
	v_lshlrev_b32_e32 v52, 2, v48
	v_pk_add_f32 v[48:49], v[60:61], v[62:63]
	v_pk_add_f32 v[50:51], v[58:59], v[56:57]
	v_cmp_lt_i32_e32 vcc, v185, v179
	v_pk_add_f32 v[48:49], v[48:49], v[50:51]
	ds_bpermute_b32 v50, v52, v48
	ds_bpermute_b32 v51, v52, v49
	v_cndmask_b32_e32 v52, v171, v185, vcc
	v_lshlrev_b32_e32 v52, 2, v52
	s_waitcnt lgkmcnt(0)
	v_pk_add_f32 v[48:49], v[48:49], v[50:51]
	ds_bpermute_b32 v50, v52, v48
	ds_bpermute_b32 v51, v52, v49
	s_and_saveexec_b64 s[94:95], s[8:9]
	s_cbranch_execz .LBB0_295
	v_ashrrev_i32_e32 v65, 31, v64
	s_sub_i32 s34, s78, s24
	s_waitcnt lgkmcnt(0)
	v_pk_add_f32 v[48:49], v[48:49], v[50:51]
	s_lshl_b32 s50, s34, 2
	v_lshlrev_b64 v[50:51], 8, v[64:65]
	s_ashr_i32 s51, s50, 31
	v_lshl_add_u64 v[50:51], s[76:77], 0, v[50:51]
	v_lshl_add_u64 v[50:51], s[50:51], 3, v[50:51]
	s_lshl_b32 s34, s17, 3
	v_lshl_add_u64 v[50:51], v[50:51], 0, s[34:35]
	global_store_dwordx2 v[50:51], v[48:49], off

; __device__ __forceinline__ unsigned pk2(float lo, float hi) { return pg8::cvt_pk_bf16(lo, hi); }
; __device__ __forceinline__ float gelu_tanh(float x) { const float u = 1.5957691216057308f * (x + 0.044715f * x * x * x); return x * sigmoidf_(u); }
;     __device__ __forceinline__ void operator()(const f32x4 (&acc)[2][2][4][2], const pg8::Unit& u, int wr, int wc, int fr, int fq) const {
;     ...
;                 const int row = row0 + ai * 128 + m * 16;
;                 bf16_t* rowp = O + (size_t)row * ldc + col0;
;                 float s = 0.f, ss = 0.f;
; #pragma unroll
;                 for (int bj = 0; bj < 2; ++bj) {
;                     f32x4 v0 = acc[ai][bj][m][0] + bv[bj][0], v1 = acc[ai][bj][m][1] + bv[bj][1];
;                     if (do_gelu) {
; #pragma unroll
;                         for (int e = 0; e < 4; ++e) { v0[e] = gelu_tanh(v0[e]); v1[e] = gelu_tanh(v1[e]); }
;                     }
; #pragma unroll
;                     for (int e = 0; e < 4; ++e) { s += v0[e] + v1[e]; ss += v0[e] * v0[e] + v1[e] * v1[e]; }
;                     u32x4 w; w.x = pk2(v0[0], v0[1]); w.y = pk2(v0[2], v0[3]); w.z = pk2(v1[0], v1[1]); w.w = pk2(v1[2], v1[3]);
;                     *(u32x4*)(rowp + bj * 128) = w;
;                 }
;                 if (do_stat) {
;                     s += __shfl_xor(s, 16); s += __shfl_xor(s, 32); ss += __shfl_xor(ss, 16); ss += __shfl_xor(ss, 32);
;                     if (fq == 0) STAT[(size_t)row * 32 + (u.pn - stat_tile0) * 4 + wc] = (f32x2){s, ss};
;                 }
.LBB0_298:
	v_add_u32_e32 v48, 0xa0, v136
	s_waitcnt lgkmcnt(0)
	v_mad_i64_i32 v[50:51], s[50:51], v48, s31, 0
	v_lshl_add_u64 v[50:51], v[50:51], 1, s[58:59]
	v_lshl_add_u64 v[50:51], v[156:157], 1, v[50:51]
	v_pk_add_f32 v[22:23], v[22:23], v[30:31]
	v_pk_add_f32 v[20:21], v[20:21], v[28:29]
	v_pk_add_f32 v[18:19], v[18:19], v[26:27]
	s_and_b64 vcc, exec, s[12:13]
	v_pk_add_f32 v[16:17], v[16:17], v[24:25]
	v_cvt_pk_bf16_f32 v52, v36, v37
	v_cvt_pk_bf16_f32 v53, v38, v39
	v_cvt_pk_bf16_f32 v54, v32, v33
	v_cvt_pk_bf16_f32 v55, v34, v35
	ds_bpermute_b32 v240, v238, v50
	ds_bpermute_b32 v241, v238, v51
	ds_bpermute_b32 v242, v238, v52
	ds_bpermute_b32 v243, v238, v53
	ds_bpermute_b32 v244, v238, v54
	ds_bpermute_b32 v245, v238, v55
	s_waitcnt lgkmcnt(6)
	global_store_dwordx4 v[248:249], v[250:253], off offset:256
	s_cbranch_vccnz .LBB0_300
	v_mul_f32_e32 v49, 0x3d372713, v20
	v_mul_f32_e32 v49, v20, v49
	v_fma_f32 v49, v20, v49, v20
	v_mul_f32_e32 v49, 0x3fcc422a, v49
	v_mul_f32_e32 v49, 0xbfb8aa3b, v49
	v_exp_f32_e32 v49, v49
	v_mov_b32_e32 v53, v21
	v_mov_b32_e32 v55, v17
	v_add_f32_e32 v49, 1.0, v49
	v_rcp_f32_e32 v52, v49
	v_mul_f32_e32 v49, 0x3d372713, v16
	v_mul_f32_e32 v49, v16, v49
	v_fma_f32 v49, v16, v49, v16
	v_mul_f32_e32 v49, 0x3fcc422a, v49
	v_mul_f32_e32 v49, 0xbfb8aa3b, v49
	v_exp_f32_e32 v49, v49
	s_nop 0
	v_add_f32_e32 v49, 1.0, v49
	v_rcp_f32_e32 v54, v49
	v_mul_f32_e32 v49, 0x3d372713, v21
	v_mul_f32_e32 v49, v21, v49
	v_fmac_f32_e32 v53, v53, v49
	v_mul_f32_e32 v49, 0x3fcc422a, v53
	v_mul_f32_e32 v49, 0xbfb8aa3b, v49
	v_exp_f32_e32 v49, v49
	s_nop 0
	v_add_f32_e32 v49, 1.0, v49
	v_rcp_f32_e32 v53, v49
	v_mul_f32_e32 v49, 0x3d372713, v17
	v_mul_f32_e32 v49, v17, v49
	v_fmac_f32_e32 v55, v55, v49
	v_mul_f32_e32 v49, 0x3fcc422a, v55
	v_mul_f32_e32 v49, 0xbfb8aa3b, v49
	v_exp_f32_e32 v49, v49
	v_pk_mul_f32 v[20:21], v[20:21], v[52:53]
	v_add_f32_e32 v49, 1.0, v49
	v_rcp_f32_e32 v55, v49
	v_mul_f32_e32 v49, 0x3d372713, v22
	v_mul_f32_e32 v49, v22, v49
	v_fma_f32 v49, v22, v49, v22
	v_mul_f32_e32 v49, 0x3fcc422a, v49
	v_mul_f32_e32 v49, 0xbfb8aa3b, v49
	v_exp_f32_e32 v49, v49
	v_pk_mul_f32 v[16:17], v[16:17], v[54:55]
	v_add_f32_e32 v49, 1.0, v49
	v_rcp_f32_e32 v56, v49
	v_mul_f32_e32 v49, 0x3d372713, v18
	v_mul_f32_e32 v49, v18, v49
	v_fma_f32 v49, v18, v49, v18
	v_mul_f32_e32 v49, 0x3fcc422a, v49
	v_mul_f32_e32 v49, 0xbfb8aa3b, v49
	v_exp_f32_e32 v49, v49
	s_nop 0
	v_add_f32_e32 v49, 1.0, v49
	v_rcp_f32_e32 v58, v49
	v_mul_f32_e32 v49, 0x3d372713, v23
	v_mul_f32_e32 v49, v23, v49
	v_fma_f32 v49, v23, v49, v23
	v_mul_f32_e32 v49, 0x3fcc422a, v49
	v_mul_f32_e32 v49, 0xbfb8aa3b, v49
	v_exp_f32_e32 v49, v49
	s_nop 0
	v_add_f32_e32 v49, 1.0, v49
	v_rcp_f32_e32 v57, v49
	v_mul_f32_e32 v49, 0x3d372713, v19
	v_mul_f32_e32 v49, v19, v49
	v_fma_f32 v49, v19, v49, v19
	v_mul_f32_e32 v49, 0x3fcc422a, v49
	v_mul_f32_e32 v49, 0xbfb8aa3b, v49
	v_exp_f32_e32 v49, v49
	v_pk_mul_f32 v[22:23], v[22:23], v[56:57]
	v_add_f32_e32 v49, 1.0, v49
	v_rcp_f32_e32 v59, v49
	s_nop 0
	v_pk_mul_f32 v[18:19], v[18:19], v[58:59]
.LBB0_300:
	s_and_b64 vcc, exec, s[14:15]
	v_cvt_pk_bf16_f32 v52, v20, v21
	v_cvt_pk_bf16_f32 v53, v22, v23
	v_cvt_pk_bf16_f32 v54, v16, v17
	v_cvt_pk_bf16_f32 v55, v18, v19
	ds_bpermute_b32 v248, v238, v50
	ds_bpermute_b32 v249, v238, v51
	ds_bpermute_b32 v250, v238, v52
	ds_bpermute_b32 v251, v238, v53
	ds_bpermute_b32 v252, v238, v54
	ds_bpermute_b32 v253, v238, v55
	s_waitcnt lgkmcnt(6)
	global_store_dwordx4 v[240:241], v[242:245], off
	s_cbranch_vccnz .LBB0_304
	v_add_f32_e32 v49, v36, v32
	v_mul_f32_e32 v32, v32, v32
	v_fmac_f32_e32 v32, v36, v36
	v_add_f32_e32 v36, v37, v33
	v_mul_f32_e32 v33, v33, v33
	v_fmac_f32_e32 v33, v37, v37
	v_add_f32_e32 v49, 0, v49
	v_add_f32_e32 v32, v32, v33
	v_add_f32_e32 v33, v38, v34
	v_mul_f32_e32 v34, v34, v34
	v_add_f32_e32 v36, v36, v49
	v_fmac_f32_e32 v34, v38, v38
	v_add_f32_e32 v33, v33, v36
	v_add_f32_e32 v32, v34, v32
	v_add_f32_e32 v34, v39, v35
	v_add_f32_e32 v49, v34, v33
	v_mul_f32_e32 v33, v35, v35
	v_fmac_f32_e32 v33, v39, v39
	v_add_f32_e32 v34, v33, v32
	v_pk_mul_f32 v[32:33], v[16:17], v[16:17]
	v_mov_b32_e32 v35, v18
	v_pk_fma_f32 v[32:33], v[20:21], v[20:21], v[32:33]
	v_pk_add_f32 v[16:17], v[20:21], v[16:17]
	v_add_f32_e32 v32, v34, v32
	v_add_f32_e32 v33, v33, v32
	v_mov_b32_e32 v34, v22
	v_mul_f32_e32 v32, v22, v22
	v_pk_fma_f32 v[34:35], v[34:35], v[34:35], v[32:33] op_sel_hi:[1,1,0]
	v_pk_add_f32 v[36:37], v[22:23], v[18:19]
	v_pk_mul_f32 v[38:39], v[22:23], v[22:23]
	v_add_f32_e32 v16, v49, v16
	v_cmp_lt_i32_e32 vcc, v184, v179
	v_mov_b32_e32 v37, v39
	v_mul_f32_e32 v39, v19, v19
	v_add_f32_e32 v38, v17, v16
	v_cndmask_b32_e32 v16, v171, v184, vcc
	v_mov_b32_e32 v34, v23
	v_mov_b32_e32 v32, v19
	v_lshlrev_b32_e32 v20, 2, v16
	v_pk_add_f32 v[16:17], v[36:37], v[38:39]
	v_pk_add_f32 v[18:19], v[34:35], v[32:33]
	v_cmp_lt_i32_e32 vcc, v185, v179
	v_pk_add_f32 v[16:17], v[16:17], v[18:19]
	ds_bpermute_b32 v18, v20, v16
	ds_bpermute_b32 v19, v20, v17
	v_cndmask_b32_e32 v20, v171, v185, vcc
	v_lshlrev_b32_e32 v20, 2, v20
	s_waitcnt lgkmcnt(0)
	v_pk_add_f32 v[16:17], v[16:17], v[18:19]
	ds_bpermute_b32 v18, v20, v16
	ds_bpermute_b32 v19, v20, v17
	s_and_saveexec_b64 s[94:95], s[8:9]
	s_cbranch_execz .LBB0_303
	v_ashrrev_i32_e32 v49, 31, v48
	s_sub_i32 s34, s78, s24
	s_waitcnt lgkmcnt(0)
	v_pk_add_f32 v[16:17], v[16:17], v[18:19]
	s_lshl_b32 s50, s34, 2
	v_lshlrev_b64 v[18:19], 8, v[48:49]
	s_ashr_i32 s51, s50, 31
	v_lshl_add_u64 v[18:19], s[76:77], 0, v[18:19]
	v_lshl_add_u64 v[18:19], s[50:51], 3, v[18:19]
	s_lshl_b32 s34, s17, 3
	v_lshl_add_u64 v[18:19], v[18:19], 0, s[34:35]
	global_store_dwordx2 v[18:19], v[16:17], off

; __device__ __forceinline__ unsigned pk2(float lo, float hi) { return pg8::cvt_pk_bf16(lo, hi); }
; __device__ __forceinline__ float gelu_tanh(float x) { const float u = 1.5957691216057308f * (x + 0.044715f * x * x * x); return x * sigmoidf_(u); }
;     __device__ __forceinline__ void operator()(const f32x4 (&acc)[2][2][4][2], const pg8::Unit& u, int wr, int wc, int fr, int fq) const {
;     ...
;                 const int row = row0 + ai * 128 + m * 16;
;                 bf16_t* rowp = O + (size_t)row * ldc + col0;
;                 float s = 0.f, ss = 0.f;
; #pragma unroll
;                 for (int bj = 0; bj < 2; ++bj) {
;                     f32x4 v0 = acc[ai][bj][m][0] + bv[bj][0], v1 = acc[ai][bj][m][1] + bv[bj][1];
;                     if (do_gelu) {
; #pragma unroll
;                         for (int e = 0; e < 4; ++e) { v0[e] = gelu_tanh(v0[e]); v1[e] = gelu_tanh(v1[e]); }
;                     }
; #pragma unroll
;                     for (int e = 0; e < 4; ++e) { s += v0[e] + v1[e]; ss += v0[e] * v0[e] + v1[e] * v1[e]; }
;                     u32x4 w; w.x = pk2(v0[0], v0[1]); w.y = pk2(v0[2], v0[3]); w.z = pk2(v1[0], v1[1]); w.w = pk2(v1[2], v1[3]);
;                     *(u32x4*)(rowp + bj * 128) = w;
;                 }
;                 if (do_stat) {
;                     s += __shfl_xor(s, 16); s += __shfl_xor(s, 32); ss += __shfl_xor(ss, 16); ss += __shfl_xor(ss, 32);
;                     if (fq == 0) STAT[(size_t)row * 32 + (u.pn - stat_tile0) * 4 + wc] = (f32x2){s, ss};
;                 }
.LBB0_306:
	v_add_u32_e32 v16, 0xb0, v136
	s_waitcnt lgkmcnt(0)
	v_mad_i64_i32 v[18:19], s[50:51], v16, s31, 0
	v_lshl_add_u64 v[18:19], v[18:19], 1, s[58:59]
	v_lshl_add_u64 v[18:19], v[156:157], 1, v[18:19]
	v_pk_add_f32 v[6:7], v[6:7], v[30:31]
	v_pk_add_f32 v[4:5], v[4:5], v[28:29]
	v_pk_add_f32 v[2:3], v[2:3], v[26:27]
	s_and_b64 vcc, exec, s[12:13]
	v_pk_add_f32 v[0:1], v[0:1], v[24:25]
	v_cvt_pk_bf16_f32 v20, v12, v13
	v_cvt_pk_bf16_f32 v21, v14, v15
	v_cvt_pk_bf16_f32 v22, v8, v9
	v_cvt_pk_bf16_f32 v23, v10, v11
	ds_bpermute_b32 v240, v238, v18
	ds_bpermute_b32 v241, v238, v19
	ds_bpermute_b32 v242, v238, v20
	ds_bpermute_b32 v243, v238, v21
	ds_bpermute_b32 v244, v238, v22
	ds_bpermute_b32 v245, v238, v23
	s_waitcnt lgkmcnt(6)
	global_store_dwordx4 v[248:249], v[250:253], off offset:256
	s_cbranch_vccnz .LBB0_308
	v_mul_f32_e32 v17, 0x3d372713, v4
	v_mul_f32_e32 v17, v4, v17
	v_fma_f32 v17, v4, v17, v4
	v_mul_f32_e32 v17, 0x3fcc422a, v17
	v_mul_f32_e32 v17, 0xbfb8aa3b, v17
	v_exp_f32_e32 v17, v17
	v_mov_b32_e32 v21, v5
	v_mov_b32_e32 v23, v1
	v_add_f32_e32 v17, 1.0, v17
	v_rcp_f32_e32 v20, v17
	v_mul_f32_e32 v17, 0x3d372713, v0
	v_mul_f32_e32 v17, v0, v17
	v_fma_f32 v17, v0, v17, v0
	v_mul_f32_e32 v17, 0x3fcc422a, v17
	v_mul_f32_e32 v17, 0xbfb8aa3b, v17
	v_exp_f32_e32 v17, v17
	s_nop 0
	v_add_f32_e32 v17, 1.0, v17
	v_rcp_f32_e32 v22, v17
	v_mul_f32_e32 v17, 0x3d372713, v5
	v_mul_f32_e32 v17, v5, v17
	v_fmac_f32_e32 v21, v21, v17
	v_mul_f32_e32 v17, 0x3fcc422a, v21
	v_mul_f32_e32 v17, 0xbfb8aa3b, v17
	v_exp_f32_e32 v17, v17
	s_nop 0
	v_add_f32_e32 v17, 1.0, v17
	v_rcp_f32_e32 v21, v17
	v_mul_f32_e32 v17, 0x3d372713, v1
	v_mul_f32_e32 v17, v1, v17
	v_fmac_f32_e32 v23, v23, v17
	v_mul_f32_e32 v17, 0x3fcc422a, v23
	v_mul_f32_e32 v17, 0xbfb8aa3b, v17
	v_exp_f32_e32 v17, v17
	v_pk_mul_f32 v[4:5], v[4:5], v[20:21]
	v_add_f32_e32 v17, 1.0, v17
	v_rcp_f32_e32 v23, v17
	v_mul_f32_e32 v17, 0x3d372713, v6
	v_mul_f32_e32 v17, v6, v17
	v_fma_f32 v17, v6, v17, v6
	v_mul_f32_e32 v17, 0x3fcc422a, v17
	v_mul_f32_e32 v17, 0xbfb8aa3b, v17
	v_exp_f32_e32 v17, v17
	v_pk_mul_f32 v[0:1], v[0:1], v[22:23]
	v_add_f32_e32 v17, 1.0, v17
	v_rcp_f32_e32 v24, v17
	v_mul_f32_e32 v17, 0x3d372713, v2
	v_mul_f32_e32 v17, v2, v17
	v_fma_f32 v17, v2, v17, v2
	v_mul_f32_e32 v17, 0x3fcc422a, v17
	v_mul_f32_e32 v17, 0xbfb8aa3b, v17
	v_exp_f32_e32 v17, v17
	s_nop 0
	v_add_f32_e32 v17, 1.0, v17
	v_rcp_f32_e32 v26, v17
	v_mul_f32_e32 v17, 0x3d372713, v7
	v_mul_f32_e32 v17, v7, v17
	v_fma_f32 v17, v7, v17, v7
	v_mul_f32_e32 v17, 0x3fcc422a, v17
	v_mul_f32_e32 v17, 0xbfb8aa3b, v17
	v_exp_f32_e32 v17, v17
	s_nop 0
	v_add_f32_e32 v17, 1.0, v17
	v_rcp_f32_e32 v25, v17
	v_mul_f32_e32 v17, 0x3d372713, v3
	v_mul_f32_e32 v17, v3, v17
	v_fma_f32 v17, v3, v17, v3
	v_mul_f32_e32 v17, 0x3fcc422a, v17
	v_mul_f32_e32 v17, 0xbfb8aa3b, v17
	v_exp_f32_e32 v17, v17
	v_pk_mul_f32 v[6:7], v[6:7], v[24:25]
	v_add_f32_e32 v17, 1.0, v17
	v_rcp_f32_e32 v27, v17
	s_nop 0
	v_pk_mul_f32 v[2:3], v[2:3], v[26:27]
.LBB0_308:
	s_and_b64 vcc, exec, s[14:15]
	v_cvt_pk_bf16_f32 v20, v4, v5
	v_cvt_pk_bf16_f32 v21, v6, v7
	v_cvt_pk_bf16_f32 v22, v0, v1
	v_cvt_pk_bf16_f32 v23, v2, v3
	ds_bpermute_b32 v248, v238, v18
	ds_bpermute_b32 v249, v238, v19
	ds_bpermute_b32 v250, v238, v20
	ds_bpermute_b32 v251, v238, v21
	ds_bpermute_b32 v252, v238, v22
	ds_bpermute_b32 v253, v238, v23
	s_waitcnt lgkmcnt(6)
	global_store_dwordx4 v[240:241], v[242:245], off
	s_waitcnt lgkmcnt(0)
	global_store_dwordx4 v[248:249], v[250:253], off offset:256
	s_cbranch_vccnz .LBB0_312
	v_add_f32_e32 v17, v12, v8
	v_mul_f32_e32 v8, v8, v8
	v_fmac_f32_e32 v8, v12, v12
	v_add_f32_e32 v12, v13, v9
	v_mul_f32_e32 v9, v9, v9
	v_fmac_f32_e32 v9, v13, v13
	v_add_f32_e32 v17, 0, v17
	v_add_f32_e32 v8, v8, v9
	v_add_f32_e32 v9, v14, v10
	v_mul_f32_e32 v10, v10, v10
	v_add_f32_e32 v12, v12, v17
	v_fmac_f32_e32 v10, v14, v14
	v_add_f32_e32 v9, v9, v12
	v_add_f32_e32 v8, v10, v8
	v_add_f32_e32 v10, v15, v11
	v_add_f32_e32 v17, v10, v9
	v_mul_f32_e32 v9, v11, v11
	v_fmac_f32_e32 v9, v15, v15
	v_add_f32_e32 v10, v9, v8
	v_pk_mul_f32 v[8:9], v[0:1], v[0:1]
	v_mov_b32_e32 v11, v2
	v_pk_fma_f32 v[8:9], v[4:5], v[4:5], v[8:9]
	v_pk_add_f32 v[0:1], v[4:5], v[0:1]
	v_add_f32_e32 v8, v10, v8
	v_add_f32_e32 v9, v9, v8
	v_mov_b32_e32 v10, v6
	v_mul_f32_e32 v8, v6, v6
	v_pk_fma_f32 v[10:11], v[10:11], v[10:11], v[8:9] op_sel_hi:[1,1,0]
	v_pk_add_f32 v[12:13], v[6:7], v[2:3]
	v_pk_mul_f32 v[14:15], v[6:7], v[6:7]
	v_add_f32_e32 v0, v17, v0
	v_cmp_lt_i32_e32 vcc, v184, v179
	v_mov_b32_e32 v13, v15
	v_mul_f32_e32 v15, v3, v3
	v_add_f32_e32 v14, v1, v0
	v_cndmask_b32_e32 v0, v171, v184, vcc
	v_mov_b32_e32 v10, v7
	v_mov_b32_e32 v8, v3
	v_lshlrev_b32_e32 v4, 2, v0
	v_pk_add_f32 v[0:1], v[12:13], v[14:15]
	v_pk_add_f32 v[2:3], v[10:11], v[8:9]
	v_cmp_lt_i32_e32 vcc, v185, v179
	v_pk_add_f32 v[0:1], v[0:1], v[2:3]
	ds_bpermute_b32 v2, v4, v0
	ds_bpermute_b32 v3, v4, v1
	v_cndmask_b32_e32 v4, v171, v185, vcc
	v_lshlrev_b32_e32 v4, 2, v4
	s_waitcnt lgkmcnt(0)
	v_pk_add_f32 v[0:1], v[0:1], v[2:3]
	ds_bpermute_b32 v2, v4, v0
	ds_bpermute_b32 v3, v4, v1
	s_and_saveexec_b64 s[12:13], s[8:9]
	s_cbranch_execz .LBB0_311
	v_ashrrev_i32_e32 v17, 31, v16
	s_sub_i32 s14, s78, s24
	s_waitcnt lgkmcnt(0)
	v_pk_add_f32 v[0:1], v[0:1], v[2:3]
	s_lshl_b32 s14, s14, 2
	v_lshlrev_b64 v[2:3], 8, v[16:17]
	s_ashr_i32 s15, s14, 31
	v_lshl_add_u64 v[2:3], s[76:77], 0, v[2:3]
	v_lshl_add_u64 v[2:3], s[14:15], 3, v[2:3]
	s_lshl_b32 s34, s17, 3
	v_lshl_add_u64 v[2:3], v[2:3], 0, s[34:35]
	global_store_dwordx2 v[2:3], v[0:1], off
